# scan loop: static s_setprio 1 for waves 4-7 (younger half), reset at loop exit
# baseline (speedup 1.0000x reference)
.LBB0_1472:
	v_add_u32_e32 v174, v166, v160
	v_add_u32_e32 v175, v167, v160
	ds_read_b128 v[52:55], v132
	ds_read_b128 v[60:63], v174 offset:17408
	ds_read_b128 v[64:67], v175 offset:17408
	v_add_u32_e32 v173, v161, v160
	ds_read_b128 v[56:59], v173
	ds_read_b128 v[68:71], v133
	ds_read_b128 v[72:75], v174 offset:17472
	v_readfirstlane_b32 s98, v179
	s_nop 3
	s_lshr_b32 s98, s98, 6
	s_cmp_ge_u32 s98, 4
	s_cbranch_scc0 .Lscan_prio_skip
	s_setprio 1

.LBB0_1500:
	s_setprio 0
	ds_read_b128 v[16:19], v174 offset:17408
	ds_read_b128 v[20:23], v173
	ds_read_b128 v[24:27], v132
	ds_read_b128 v[28:31], v175 offset:17408
	ds_read_b128 v[32:35], v133
	ds_read_b128 v[36:39], v174 offset:17472
	s_waitcnt lgkmcnt(4)
	v_mfma_f32_16x16x32_bf16 v[16:19], v[16:19], v[20:23], 0
	v_readlane_b32 s0, v252, 23
	s_waitcnt lgkmcnt(3)
	v_mfma_f32_16x16x32_bf16 v[24:27], v[24:27], v[20:23], 0
	s_waitcnt lgkmcnt(2)
	v_mfma_f32_16x16x32_bf16 v[28:31], v[28:31], v[20:23], 0
	s_waitcnt lgkmcnt(1)
	v_mfma_f32_16x16x32_bf16 v[20:23], v[32:35], v[20:23], 0
	ds_read_b128 v[32:35], v173 offset:64
	s_waitcnt lgkmcnt(0)
	v_mfma_f32_16x16x32_bf16 v[16:19], v[36:39], v[32:35], v[16:19]
	ds_read_b128 v[36:39], v132 offset:64
	s_waitcnt lgkmcnt(0)
	v_mfma_f32_16x16x32_bf16 v[24:27], v[36:39], v[32:35], v[24:27]
	ds_read_b128 v[36:39], v175 offset:17472
	s_waitcnt lgkmcnt(0)
	v_mfma_f32_16x16x32_bf16 v[28:31], v[36:39], v[32:35], v[28:31]
	ds_read_b128 v[36:39], v133 offset:64
	ds_read_b128 v[40:43], v174 offset:17536
	s_waitcnt lgkmcnt(1)
	v_mfma_f32_16x16x32_bf16 v[20:23], v[36:39], v[32:35], v[20:23]
	ds_read_b128 v[32:35], v173 offset:128
	ds_read_b128 v[36:39], v132 offset:128
	s_waitcnt lgkmcnt(1)
	v_mfma_f32_16x16x32_bf16 v[16:19], v[40:43], v[32:35], v[16:19]
	ds_read_b128 v[40:43], v175 offset:17536
	s_waitcnt lgkmcnt(1)
	v_mfma_f32_16x16x32_bf16 v[24:27], v[36:39], v[32:35], v[24:27]
	ds_read_b128 v[36:39], v133 offset:128
	s_waitcnt lgkmcnt(1)
	v_mfma_f32_16x16x32_bf16 v[28:31], v[40:43], v[32:35], v[28:31]
	ds_read_b128 v[40:43], v174 offset:17600
	s_waitcnt lgkmcnt(1)
	v_mfma_f32_16x16x32_bf16 v[20:23], v[36:39], v[32:35], v[20:23]
	ds_read_b128 v[32:35], v173 offset:192
	v_mov_b32_e32 v36, s0
	ds_read_b32 v58, v36
	s_waitcnt lgkmcnt(1)
	v_mfma_f32_16x16x32_bf16 v[48:51], v[40:43], v[32:35], v[16:19]
	s_nop 2
	ds_read_b128 v[16:19], v132 offset:192
	s_waitcnt lgkmcnt(0)
	v_mfma_f32_16x16x32_bf16 v[16:19], v[16:19], v[32:35], v[24:27]
	s_nop 2
	ds_read_b128 v[24:27], v175 offset:17600
	s_waitcnt lgkmcnt(0)
	v_mfma_f32_16x16x32_bf16 v[24:27], v[24:27], v[32:35], v[28:31]
	s_nop 2
	ds_read_b128 v[28:31], v133 offset:192
	s_waitcnt lgkmcnt(0)
	v_mfma_f32_16x16x32_bf16 v[20:23], v[28:31], v[32:35], v[20:23]
	v_add_u32_e32 v28, 0x23100, v146
	v_add_u32_e32 v56, v28, v148
	ds_read_b128 v[28:31], v56
	ds_read_b128 v[32:35], v190 offset:62464
	ds_read_b128 v[36:39], v56 offset:2304
	ds_read_b128 v[40:43], v56 offset:4608
	ds_read_b128 v[44:47], v56 offset:6912
	v_add_u32_e32 v57, 0x27900, v96
	s_waitcnt lgkmcnt(3)
	v_mfma_f32_16x16x32_bf16 v[28:31], v[28:31], v[32:35], 0
	s_waitcnt lgkmcnt(2)
	v_mfma_f32_16x16x32_bf16 v[36:39], v[36:39], v[32:35], 0
	s_waitcnt lgkmcnt(1)
	v_mfma_f32_16x16x32_bf16 v[52:55], v[40:43], v[32:35], 0
	ds_read_b128 v[40:43], v159
	s_waitcnt lgkmcnt(1)
	v_mfma_f32_16x16x32_bf16 v[44:47], v[44:47], v[32:35], 0
	ds_read_b128 v[32:35], v192 offset:53248
	ds_read_b128 v[66:69], v188 offset:53248
	s_waitcnt lgkmcnt(1)
	v_mfma_f32_16x16x32_bf16 v[70:73], v[40:43], v[32:35], 0
	ds_read_b128 v[32:35], v56 offset:64
	ds_read_b128 v[74:77], v190 offset:62528
	ds_read_b32 v59, v57
	s_waitcnt lgkmcnt(3)
	v_mfma_f32_16x16x32_bf16 v[78:81], v[40:43], v[66:69], 0
	ds_read_b128 v[66:69], v56 offset:2368
	s_waitcnt lgkmcnt(2)
	v_mfma_f32_16x16x32_bf16 v[40:43], v[32:35], v[74:77], v[28:31]
	s_nop 2
	ds_read_b128 v[28:31], v56 offset:4672
	s_waitcnt lgkmcnt(1)
	v_mfma_f32_16x16x32_bf16 v[36:39], v[66:69], v[74:77], v[36:39]
	ds_read_b128 v[66:69], v56 offset:6976
	s_waitcnt lgkmcnt(1)
	v_mfma_f32_16x16x32_bf16 v[32:35], v[28:31], v[74:77], v[52:55]
	s_nop 2
	ds_read_b128 v[52:55], v159 offset:64
	s_waitcnt lgkmcnt(1)
	v_mfma_f32_16x16x32_bf16 v[28:31], v[66:69], v[74:77], v[44:47]
	ds_read_b128 v[74:77], v188 offset:53312
	v_mov_b32_e32 v66, 0
	v_mov_b32_e32 v67, 0
	ds_read_b128 v[44:47], v192 offset:53312
	s_waitcnt lgkmcnt(0)
	v_mfma_f32_16x16x32_bf16 v[44:47], v[52:55], v[44:47], v[70:73]
	v_mfma_f32_16x16x32_bf16 v[52:55], v[52:55], v[74:77], v[78:81]
	s_and_saveexec_b64 s[0:1], s[58:59]
	s_cbranch_execz .LBB0_1524
	v_add_u32_e32 v67, 0, v143
	v_add_u32_e32 v67, 0x27900, v67
	ds_read_b32 v67, v67
	s_waitcnt lgkmcnt(0)
	v_sub_f32_e32 v67, v59, v67
	v_mul_f32_e32 v67, 0x3fb8aa3b, v67
	v_exp_f32_e32 v67, v67
	s_nop 0
	v_mul_f32_e32 v67, v48, v67
	s_or_b64 exec, exec, s[0:1]
	v_mov_b32_e32 v68, 0
	s_and_saveexec_b64 s[0:1], s[56:57]
	s_cbranch_execnz .LBB0_1525
